# conformer-conv LayerNorm wave sums: 96 ds_bpermute hops replaced by DPP (quad_perm / row_half_mirror / row_ror) and v_permlane16/32_swap lane exchanges
# speedup vs baseline: 1.0004x; 1.0004x over previous
; #define LAS __attribute__((address_space(3)))
; __device__ __forceinline__ float wave_sum(float v) { v += __shfl_xor(v, 32); v += __shfl_xor(v, 16); v += __shfl_xor(v, 8); v += __shfl_xor(v, 4); v += __shfl_xor(v, 2); v += __shfl_xor(v, 1); return v; }
; __device__ void conv_unit(LAS unsigned char* lds, const bf16_t* __restrict__ Z, bf16_t* __restrict__ MIX, int unit,
;                           const float* __restrict__ ccw, const float* __restrict__ ccb, const float* __restrict__ lng, const float* __restrict__ lnb, const float* __restrict__ scw) {
;     ...
;     { const int wid = tid >> 6, lane = tid & 63; const f32x4 gg = *(const f32x4*)(lng + lane * 4), bb = *(const f32x4*)(lnb + lane * 4);
;       for (int j = 0; j < 8; ++j) { const int tok = wid * 8 + j; const f32x4 y = *(LAS const f32x4*)(ub + tok * 256 + lane * 4);
;           const float mean = wave_sum(y[0] + y[1] + y[2] + y[3]) * (1.f / 256.f); const f32x4 d = y - mean;
;           const float var = wave_sum(d[0] * d[0] + d[1] * d[1] + d[2] * d[2] + d[3] * d[3]) * (1.f / 256.f), rstd = rsqrtf(var + 1e-6f);
.LBB0_143:
	s_barrier
	ds_write2st64_b32 v103, v4, v5 offset1:4
	ds_write2st64_b32 v103, v6, v7 offset0:8 offset1:12
	ds_write2st64_b32 v103, v8, v9 offset0:16 offset1:20
	ds_write2st64_b32 v103, v10, v11 offset0:24 offset1:28
	ds_write2st64_b32 v103, v12, v13 offset0:32 offset1:36
	ds_write2st64_b32 v103, v14, v15 offset0:40 offset1:44
	ds_write2st64_b32 v103, v16, v17 offset0:48 offset1:52
	ds_write2st64_b32 v103, v18, v19 offset0:56 offset1:60
	ds_write2st64_b32 v103, v20, v21 offset0:64 offset1:68
	ds_write2st64_b32 v103, v22, v23 offset0:72 offset1:76
	ds_write2st64_b32 v103, v24, v25 offset0:80 offset1:84
	ds_write2st64_b32 v103, v26, v27 offset0:88 offset1:92
	ds_write2st64_b32 v103, v28, v29 offset0:96 offset1:100
	ds_write2st64_b32 v103, v30, v31 offset0:104 offset1:108
	ds_write2st64_b32 v103, v32, v33 offset0:112 offset1:116
	ds_write2st64_b32 v103, v34, v35 offset0:120 offset1:124
	v_and_b32_e32 v25, 0xfc, v102
	v_lshlrev_b32_e32 v6, 2, v25
	v_ashrrev_i32_e32 v22, 3, v100
	v_and_b32_e32 v24, -8, v22
	v_add_u32_e32 v23, 0, v6
	v_lshl_add_u32 v2, v24, 10, v23
	s_waitcnt lgkmcnt(0)
	s_barrier
	ds_read_b128 v[26:29], v2
	v_or_b32_e32 v44, 1, v24
	v_lshl_add_u32 v2, v44, 10, v23
	ds_read_b128 v[12:15], v2
	s_mov_b32 s10, 0x358637bd
	s_waitcnt lgkmcnt(0)
	v_add_f32_e32 v2, v26, v27
	v_add_f32_e32 v2, v28, v2
	v_add_f32_e32 v2, v29, v2
	v_mov_b32_e32 v120, v2
	v_mov_b32_e32 v3, v2
	s_nop 1
	v_permlane32_swap_b32_e32 v120, v3
	s_nop 1
	v_permlane32_swap_b32_e32 v3, v120
	s_nop 0
	s_waitcnt lgkmcnt(0)
	v_add_f32_e32 v4, v12, v13
	v_add_f32_e32 v4, v14, v4
	v_add_f32_e32 v4, v15, v4
	v_mov_b32_e32 v120, v4
	v_mov_b32_e32 v5, v4
	s_nop 1
	v_permlane32_swap_b32_e32 v120, v5
	s_nop 1
	v_permlane32_swap_b32_e32 v5, v120
	s_nop 0
	s_waitcnt lgkmcnt(0)
	v_add_f32_e32 v2, v2, v3
	v_mov_b32_e32 v120, v2
	v_mov_b32_e32 v3, v2
	s_nop 1
	v_permlane16_swap_b32_e32 v120, v3
	s_nop 1
	v_permlane16_swap_b32_e32 v3, v120
	s_nop 0
	v_readlane_b32 s14, v252, 18
	v_readlane_b32 s15, v252, 19
	s_waitcnt lgkmcnt(0)
	v_add_f32_e32 v4, v4, v5
	v_mov_b32_e32 v120, v4
	v_mov_b32_e32 v5, v4
	s_nop 1
	v_permlane16_swap_b32_e32 v120, v5
	s_nop 1
	v_permlane16_swap_b32_e32 v5, v120
	s_nop 0
	s_waitcnt lgkmcnt(0)
	v_add_f32_e32 v2, v2, v3
	s_nop 1
	v_mov_b32_dpp v3, v2 row_ror:8 row_mask:0xf bank_mask:0xf
	v_or_b32_e32 v45, 3, v24
	v_readlane_b32 s20, v252, 20
	s_waitcnt lgkmcnt(0)
	v_add_f32_e32 v4, v4, v5
	s_nop 1
	v_mov_b32_dpp v5, v4 row_ror:8 row_mask:0xf bank_mask:0xf
	s_waitcnt lgkmcnt(0)
	v_add_f32_e32 v2, v2, v3
	s_nop 1
	v_mov_b32_dpp v121, v2 quad_perm:[3,2,1,0] row_mask:0xf bank_mask:0xf
	s_nop 1
	v_mov_b32_dpp v3, v121 row_half_mirror row_mask:0xf bank_mask:0xf
	v_readlane_b32 s21, v252, 21
	s_waitcnt lgkmcnt(0)
	v_add_f32_e32 v4, v4, v5
	s_nop 1
	v_mov_b32_dpp v121, v4 quad_perm:[3,2,1,0] row_mask:0xf bank_mask:0xf
	s_nop 1
	v_mov_b32_dpp v5, v121 row_half_mirror row_mask:0xf bank_mask:0xf
	s_waitcnt lgkmcnt(0)
	v_add_f32_e32 v2, v2, v3
	s_nop 1
	v_mov_b32_dpp v3, v2 quad_perm:[2,3,0,1] row_mask:0xf bank_mask:0xf
	s_waitcnt lgkmcnt(0)
	v_add_f32_e32 v16, v4, v5
	s_nop 1
	v_mov_b32_dpp v17, v16 quad_perm:[2,3,0,1] row_mask:0xf bank_mask:0xf
	s_waitcnt lgkmcnt(0)
	v_add_f32_e32 v10, v2, v3
	global_load_dwordx4 v[2:5], v6, s[36:37]
	s_nop 0
	global_load_dwordx4 v[6:9], v6, s[38:39]
	s_nop 1
	v_mov_b32_dpp v11, v10 quad_perm:[1,0,3,2] row_mask:0xf bank_mask:0xf
	s_waitcnt lgkmcnt(0)
	v_add_f32_e32 v20, v16, v17
	s_nop 1
	v_mov_b32_dpp v21, v20 quad_perm:[1,0,3,2] row_mask:0xf bank_mask:0xf
	s_waitcnt lgkmcnt(0)
	v_add_f32_e32 v18, v10, v11
	v_fmamk_f32 v11, v18, 0xbb800000, v27
	v_fmamk_f32 v10, v18, 0xbb800000, v26
	s_waitcnt lgkmcnt(0)
	v_add_f32_e32 v20, v20, v21
	v_fmamk_f32 v31, v20, 0xbb800000, v13
	v_fmamk_f32 v30, v20, 0xbb800000, v12
	v_fmamk_f32 v29, v18, 0xbb800000, v29
	v_fmac_f32_e32 v28, 0xbb800000, v18
	v_pk_mul_f32 v[18:19], v[10:11], v[10:11]
	v_fmamk_f32 v15, v20, 0xbb800000, v15
	v_fmac_f32_e32 v14, 0xbb800000, v20
	v_pk_mul_f32 v[20:21], v[30:31], v[30:31]
	v_pk_mul_f32 v[16:17], v[28:29], v[28:29]
	v_pk_mul_f32 v[12:13], v[14:15], v[14:15]
	v_mov_b32_e32 v26, v20
	v_mov_b32_e32 v27, v18
	v_mov_b32_e32 v18, v21
	v_pk_add_f32 v[18:19], v[26:27], v[18:19]
	v_mov_b32_e32 v20, v12
	v_mov_b32_e32 v21, v16
	v_pk_add_f32 v[18:19], v[20:21], v[18:19]
	v_mov_b32_e32 v16, v13
	v_pk_add_f32 v[12:13], v[16:17], v[18:19]
	v_mov_b32_e32 v120, v13
	v_mov_b32_e32 v17, v13
	s_nop 1
	v_permlane32_swap_b32_e32 v120, v17
	s_nop 1
	v_permlane32_swap_b32_e32 v17, v120
	s_nop 0
	v_mov_b32_e32 v120, v12
	v_mov_b32_e32 v16, v12
	s_nop 1
	v_permlane32_swap_b32_e32 v120, v16
	s_nop 1
	v_permlane32_swap_b32_e32 v16, v120
	s_nop 0
	v_mov_b64_e32 v[20:21], s[10:11]
	s_mov_b32 s10, 0x3b800000
	v_add_u32_e32 v18, s17, v24
	v_ashrrev_i32_e32 v19, 31, v18
	s_waitcnt lgkmcnt(0)
	v_pk_add_f32 v[12:13], v[12:13], v[16:17]
	v_mov_b32_e32 v120, v13
	v_mov_b32_e32 v17, v13
	s_nop 1
	v_permlane16_swap_b32_e32 v120, v17
	s_nop 1
	v_permlane16_swap_b32_e32 v17, v120
	s_nop 0
	v_mov_b32_e32 v120, v12
	v_mov_b32_e32 v16, v12
	s_nop 1
	v_permlane16_swap_b32_e32 v120, v16
	s_nop 1
	v_permlane16_swap_b32_e32 v16, v120
	s_nop 0
	v_lshlrev_b64 v[18:19], 11, v[18:19]
	v_lshl_add_u64 v[26:27], s[14:15], 0, v[18:19]
	v_lshlrev_b32_e32 v18, 1, v25
	v_mov_b32_e32 v19, v1
	s_waitcnt lgkmcnt(0)
	v_pk_add_f32 v[12:13], v[12:13], v[16:17]
	s_nop 1
	v_mov_b32_dpp v17, v13 row_ror:8 row_mask:0xf bank_mask:0xf
	s_nop 1
	v_mov_b32_dpp v16, v12 row_ror:8 row_mask:0xf bank_mask:0xf
	s_waitcnt lgkmcnt(0)
; #define LAS __attribute__((address_space(3)))
; __device__ __forceinline__ unsigned cvtpk(float lo, float hi) { f32x2_t v = {lo, hi}; bf16x2_t b = __builtin_convertvector(v, bf16x2_t); return __builtin_bit_cast(unsigned, b); }
; __device__ __forceinline__ float silu_f(float g) { return g * __builtin_amdgcn_rcpf(1.f + __builtin_amdgcn_exp2f(g * -1.4426950408889634f)); }
; __device__ __forceinline__ float wave_sum(float v) { v += __shfl_xor(v, 32); v += __shfl_xor(v, 16); v += __shfl_xor(v, 8); v += __shfl_xor(v, 4); v += __shfl_xor(v, 2); v += __shfl_xor(v, 1); return v; }
; __device__ void conv_unit(LAS unsigned char* lds, const bf16_t* __restrict__ Z, bf16_t* __restrict__ MIX, int unit,
;                           const float* __restrict__ ccw, const float* __restrict__ ccb, const float* __restrict__ lng, const float* __restrict__ lnb, const float* __restrict__ scw) {
;     ...
;     { const int wid = tid >> 6, lane = tid & 63; const f32x4 gg = *(const f32x4*)(lng + lane * 4), bb = *(const f32x4*)(lnb + lane * 4);
;       for (int j = 0; j < 8; ++j) { const int tok = wid * 8 + j; const f32x4 y = *(LAS const f32x4*)(ub + tok * 256 + lane * 4);
;           const float mean = wave_sum(y[0] + y[1] + y[2] + y[3]) * (1.f / 256.f); const f32x4 d = y - mean;
;           const float var = wave_sum(d[0] * d[0] + d[1] * d[1] + d[2] * d[2] + d[3] * d[3]) * (1.f / 256.f), rstd = rsqrtf(var + 1e-6f);
;           const f32x4 z = d * rstd * gg + bb; u32x2 w; w.x = cvtpk(silu_f(z[0]), silu_f(z[1])); w.y = cvtpk(silu_f(z[2]), silu_f(z[3]));
;           *(u32x2*)(MIX + (size_t)(t0 + tok) * DM + 512 + lane * 4) = w; } }
	v_pk_add_f32 v[12:13], v[12:13], v[16:17]
	s_nop 1
	v_mov_b32_dpp v121, v13 quad_perm:[3,2,1,0] row_mask:0xf bank_mask:0xf
	s_nop 1
	v_mov_b32_dpp v17, v121 row_half_mirror row_mask:0xf bank_mask:0xf
	s_nop 1
	v_mov_b32_dpp v121, v12 quad_perm:[3,2,1,0] row_mask:0xf bank_mask:0xf
	s_nop 1
	v_mov_b32_dpp v16, v121 row_half_mirror row_mask:0xf bank_mask:0xf
	s_waitcnt lgkmcnt(0)
	v_pk_add_f32 v[12:13], v[12:13], v[16:17]
	s_nop 1
	v_mov_b32_dpp v17, v13 quad_perm:[2,3,0,1] row_mask:0xf bank_mask:0xf
	s_nop 1
	v_mov_b32_dpp v16, v12 quad_perm:[2,3,0,1] row_mask:0xf bank_mask:0xf
	s_waitcnt lgkmcnt(0)
	v_pk_add_f32 v[12:13], v[12:13], v[16:17]
	s_nop 1
	v_mov_b32_dpp v17, v13 quad_perm:[1,0,3,2] row_mask:0xf bank_mask:0xf
	s_nop 1
	v_mov_b32_dpp v16, v12 quad_perm:[1,0,3,2] row_mask:0xf bank_mask:0xf
	s_waitcnt lgkmcnt(0)
	v_pk_add_f32 v[12:13], v[12:13], v[16:17]
	s_nop 0
	v_pk_fma_f32 v[12:13], v[12:13], s[10:11], v[20:21] op_sel_hi:[1,0,0]
	s_nop 0
	v_mul_f32_e32 v16, 0x4b800000, v13
	v_cmp_gt_f32_e32 vcc, s27, v13
	s_nop 1
	v_cndmask_b32_e32 v13, v13, v16, vcc
	v_rsq_f32_e32 v13, v13
	v_lshl_add_u64 v[16:17], v[26:27], 0, v[18:19]
	v_mul_f32_e32 v25, 0x45800000, v13
	v_cndmask_b32_e32 v26, v13, v25, vcc
	v_pk_mul_f32 v[10:11], v[10:11], v[26:27] op_sel_hi:[1,0]
	v_pk_mul_f32 v[26:27], v[28:29], v[26:27] op_sel_hi:[1,0]
	s_waitcnt vmcnt(0)
	v_pk_fma_f32 v[10:11], v[2:3], v[10:11], v[6:7]
	v_pk_fma_f32 v[32:33], v[4:5], v[26:27], v[8:9]
	v_mul_f32_e32 v13, 0xbfb8aa3b, v10
	v_exp_f32_e32 v13, v13
	v_mul_f32_e32 v25, 0xbfb8aa3b, v11
	v_exp_f32_e32 v25, v25
	v_cmp_gt_f32_e32 vcc, s27, v12
	v_add_f32_e32 v13, 1.0, v13
	v_rcp_f32_e32 v26, v13
	v_add_f32_e32 v13, 1.0, v25
	v_rcp_f32_e32 v27, v13
	v_mul_f32_e32 v13, 0xbfb8aa3b, v32
	v_exp_f32_e32 v13, v13
	v_mul_f32_e32 v25, 0xbfb8aa3b, v33
	v_exp_f32_e32 v25, v25
	v_pk_mul_f32 v[34:35], v[10:11], v[26:27]
	v_add_f32_e32 v10, 1.0, v13
	v_rcp_f32_e32 v36, v10
	v_add_f32_e32 v10, 1.0, v25
	v_or_b32_e32 v25, 2, v24
	v_lshl_add_u32 v11, v25, 10, v23
	ds_read_b128 v[26:29], v11
	v_rcp_f32_e32 v37, v10
	v_mul_f32_e32 v10, 0x4b800000, v12
	v_cndmask_b32_e32 v10, v12, v10, vcc
	v_rsq_f32_e32 v38, v10
	v_lshl_add_u32 v10, v45, 10, v23
	s_waitcnt lgkmcnt(0)
	v_add_f32_e32 v39, v26, v27
	ds_read_b128 v[10:13], v10
	v_add_f32_e32 v39, v28, v39
	v_add_f32_e32 v39, v29, v39
	v_mov_b32_e32 v120, v39
	v_mov_b32_e32 v40, v39
	s_nop 1
	v_permlane32_swap_b32_e32 v120, v40
	s_nop 1
	v_permlane32_swap_b32_e32 v40, v120
	s_nop 0
	v_pk_mul_f32 v[32:33], v[32:33], v[36:37]
	s_waitcnt lgkmcnt(0)
	v_add_f32_e32 v37, v10, v11
	v_add_f32_e32 v37, v12, v37
	v_cvt_pk_bf16_f32 v34, v34, v35
	v_cvt_pk_bf16_f32 v35, v32, v33
	s_waitcnt lgkmcnt(0)
	v_add_f32_e32 v33, v39, v40
	v_add_f32_e32 v37, v13, v37
	v_mov_b32_e32 v120, v33
	v_mov_b32_e32 v36, v33
	s_nop 1
	v_permlane16_swap_b32_e32 v120, v36
	s_nop 1
	v_permlane16_swap_b32_e32 v36, v120
	s_nop 0
	v_mov_b32_e32 v120, v37
	v_mov_b32_e32 v39, v37
	s_nop 1
	v_permlane32_swap_b32_e32 v120, v39
	s_nop 1
	v_permlane32_swap_b32_e32 v39, v120
	s_nop 0
	v_mul_f32_e32 v32, 0x45800000, v38
	v_cndmask_b32_e32 v32, v38, v32, vcc
	global_store_dwordx2 v[16:17], v[34:35], off offset:1024
	s_waitcnt lgkmcnt(0)
	v_add_f32_e32 v33, v33, v36
	s_waitcnt lgkmcnt(0)
	v_add_f32_e32 v37, v37, v39
	s_nop 1
	v_mov_b32_dpp v36, v33 row_ror:8 row_mask:0xf bank_mask:0xf
	v_mov_b32_e32 v120, v37
	v_mov_b32_e32 v38, v37
	s_nop 1
	v_permlane16_swap_b32_e32 v120, v38
	s_nop 1
	v_permlane16_swap_b32_e32 v38, v120
	s_nop 0
	v_pk_mul_f32 v[30:31], v[30:31], v[32:33] op_sel_hi:[1,0]
	v_pk_mul_f32 v[14:15], v[14:15], v[32:33] op_sel_hi:[1,0]
	v_pk_fma_f32 v[30:31], v[2:3], v[30:31], v[6:7]
	s_waitcnt lgkmcnt(0)
	v_add_f32_e32 v32, v33, v36
	s_waitcnt lgkmcnt(0)
	v_add_f32_e32 v36, v37, v38
	s_nop 1
	v_mov_b32_dpp v37, v36 row_ror:8 row_mask:0xf bank_mask:0xf
	s_nop 1
	v_mov_b32_dpp v121, v32 quad_perm:[3,2,1,0] row_mask:0xf bank_mask:0xf
	s_nop 1
	v_mov_b32_dpp v33, v121 row_half_mirror row_mask:0xf bank_mask:0xf
	v_mul_f32_e32 v38, 0xbfb8aa3b, v30
	v_exp_f32_e32 v46, v38
	v_mul_f32_e32 v38, 0xbfb8aa3b, v31
	s_waitcnt lgkmcnt(0)
	v_add_f32_e32 v36, v36, v37
	s_nop 1
	v_mov_b32_dpp v121, v36 quad_perm:[3,2,1,0] row_mask:0xf bank_mask:0xf
	s_nop 1
	v_mov_b32_dpp v37, v121 row_half_mirror row_mask:0xf bank_mask:0xf
	s_waitcnt lgkmcnt(0)
	v_add_f32_e32 v32, v32, v33
	s_nop 1
	v_mov_b32_dpp v33, v32 quad_perm:[2,3,0,1] row_mask:0xf bank_mask:0xf
	v_exp_f32_e32 v47, v38
	v_pk_fma_f32 v[14:15], v[4:5], v[14:15], v[8:9]
	s_waitcnt lgkmcnt(0)
	v_add_f32_e32 v36, v36, v37
	s_nop 1
	v_mov_b32_dpp v37, v36 quad_perm:[2,3,0,1] row_mask:0xf bank_mask:0xf
	s_waitcnt lgkmcnt(0)
	v_add_f32_e32 v32, v32, v33
	s_nop 1
	v_mov_b32_dpp v33, v32 quad_perm:[1,0,3,2] row_mask:0xf bank_mask:0xf
	s_waitcnt lgkmcnt(0)
	v_add_f32_e32 v38, v36, v37
	s_nop 1
	v_mov_b32_dpp v39, v38 quad_perm:[1,0,3,2] row_mask:0xf bank_mask:0xf
	s_waitcnt lgkmcnt(0)
	v_add_f32_e32 v32, v32, v33
	v_fmamk_f32 v27, v32, 0xbb800000, v27
	v_fmamk_f32 v26, v32, 0xbb800000, v26
	v_fmamk_f32 v29, v32, 0xbb800000, v29
	s_waitcnt lgkmcnt(0)
; #define LAS __attribute__((address_space(3)))
; __device__ __forceinline__ unsigned cvtpk(float lo, float hi) { f32x2_t v = {lo, hi}; bf16x2_t b = __builtin_convertvector(v, bf16x2_t); return __builtin_bit_cast(unsigned, b); }
; __device__ __forceinline__ float silu_f(float g) { return g * __builtin_amdgcn_rcpf(1.f + __builtin_amdgcn_exp2f(g * -1.4426950408889634f)); }
; __device__ __forceinline__ float wave_sum(float v) { v += __shfl_xor(v, 32); v += __shfl_xor(v, 16); v += __shfl_xor(v, 8); v += __shfl_xor(v, 4); v += __shfl_xor(v, 2); v += __shfl_xor(v, 1); return v; }
; __device__ void conv_unit(LAS unsigned char* lds, const bf16_t* __restrict__ Z, bf16_t* __restrict__ MIX, int unit,
;                           const float* __restrict__ ccw, const float* __restrict__ ccb, const float* __restrict__ lng, const float* __restrict__ lnb, const float* __restrict__ scw) {
;     ...
;     { const int wid = tid >> 6, lane = tid & 63; const f32x4 gg = *(const f32x4*)(lng + lane * 4), bb = *(const f32x4*)(lnb + lane * 4);
;       for (int j = 0; j < 8; ++j) { const int tok = wid * 8 + j; const f32x4 y = *(LAS const f32x4*)(ub + tok * 256 + lane * 4);
;           const float mean = wave_sum(y[0] + y[1] + y[2] + y[3]) * (1.f / 256.f); const f32x4 d = y - mean;
;           const float var = wave_sum(d[0] * d[0] + d[1] * d[1] + d[2] * d[2] + d[3] * d[3]) * (1.f / 256.f), rstd = rsqrtf(var + 1e-6f);
;           const f32x4 z = d * rstd * gg + bb; u32x2 w; w.x = cvtpk(silu_f(z[0]), silu_f(z[1])); w.y = cvtpk(silu_f(z[2]), silu_f(z[3]));
;           *(u32x2*)(MIX + (size_t)(t0 + tok) * DM + 512 + lane * 4) = w; } }
	v_add_f32_e32 v38, v38, v39
	v_fmamk_f32 v11, v38, 0xbb800000, v11
	v_fmamk_f32 v10, v38, 0xbb800000, v10
	v_fmac_f32_e32 v28, 0xbb800000, v32
	v_pk_mul_f32 v[36:37], v[26:27], v[26:27]
	v_fmamk_f32 v13, v38, 0xbb800000, v13
	v_fmac_f32_e32 v12, 0xbb800000, v38
	v_pk_mul_f32 v[40:41], v[10:11], v[10:11]
	v_pk_mul_f32 v[32:33], v[28:29], v[28:29]
	v_pk_mul_f32 v[38:39], v[12:13], v[12:13]
	v_mov_b32_e32 v42, v40
	v_mov_b32_e32 v43, v36
	v_mov_b32_e32 v36, v41
	v_pk_add_f32 v[36:37], v[42:43], v[36:37]
	v_mov_b32_e32 v40, v38
	v_mov_b32_e32 v41, v32
	v_pk_add_f32 v[36:37], v[40:41], v[36:37]
	v_mov_b32_e32 v32, v39
	v_pk_add_f32 v[32:33], v[32:33], v[36:37]
	v_mov_b32_e32 v120, v33
	v_mov_b32_e32 v37, v33
	s_nop 1
	v_permlane32_swap_b32_e32 v120, v37
	s_nop 1
	v_permlane32_swap_b32_e32 v37, v120
	s_nop 0
	v_mov_b32_e32 v120, v32
	v_mov_b32_e32 v36, v32
	s_nop 1
	v_permlane32_swap_b32_e32 v120, v36
	s_nop 1
	v_permlane32_swap_b32_e32 v36, v120
	s_nop 0
	v_add_f32_e32 v38, 1.0, v46
	v_add_f32_e32 v39, 1.0, v47
	v_rcp_f32_e32 v38, v38
	v_rcp_f32_e32 v39, v39
	s_waitcnt lgkmcnt(0)
	v_pk_add_f32 v[32:33], v[32:33], v[36:37]
	v_mov_b32_e32 v120, v33
	v_mov_b32_e32 v37, v33
	s_nop 1
	v_permlane16_swap_b32_e32 v120, v37
	s_nop 1
	v_permlane16_swap_b32_e32 v37, v120
	s_nop 0
	v_mov_b32_e32 v120, v32
	v_mov_b32_e32 v36, v32
	s_nop 1
	v_permlane16_swap_b32_e32 v120, v36
	s_nop 1
	v_permlane16_swap_b32_e32 v36, v120
	s_nop 0
	v_mul_f32_e32 v40, 0xbfb8aa3b, v14
	v_mul_f32_e32 v41, 0xbfb8aa3b, v15
	v_exp_f32_e32 v40, v40
	v_exp_f32_e32 v41, v41
	s_waitcnt lgkmcnt(0)
	v_pk_add_f32 v[32:33], v[32:33], v[36:37]
	s_nop 1
	v_mov_b32_dpp v37, v33 row_ror:8 row_mask:0xf bank_mask:0xf
	s_nop 1
	v_mov_b32_dpp v36, v32 row_ror:8 row_mask:0xf bank_mask:0xf
	v_pk_mul_f32 v[16:17], v[30:31], v[38:39]
	v_add_f32_e32 v40, 1.0, v40
	v_add_f32_e32 v41, 1.0, v41
	v_rcp_f32_e32 v40, v40
	s_waitcnt lgkmcnt(0)
	v_pk_add_f32 v[32:33], v[32:33], v[36:37]
	s_nop 1
	v_mov_b32_dpp v121, v33 quad_perm:[3,2,1,0] row_mask:0xf bank_mask:0xf
	s_nop 1
	v_mov_b32_dpp v37, v121 row_half_mirror row_mask:0xf bank_mask:0xf
	s_nop 1
	v_mov_b32_dpp v121, v32 quad_perm:[3,2,1,0] row_mask:0xf bank_mask:0xf
	s_nop 1
	v_mov_b32_dpp v36, v121 row_half_mirror row_mask:0xf bank_mask:0xf
	v_rcp_f32_e32 v41, v41
	v_cvt_pk_bf16_f32 v16, v16, v17
	v_or_b32_e32 v42, 5, v24
	s_waitcnt lgkmcnt(0)
	v_pk_add_f32 v[30:31], v[32:33], v[36:37]
	s_nop 1
	v_mov_b32_dpp v33, v31 quad_perm:[2,3,0,1] row_mask:0xf bank_mask:0xf
	s_nop 1
	v_mov_b32_dpp v32, v30 quad_perm:[2,3,0,1] row_mask:0xf bank_mask:0xf
	v_pk_mul_f32 v[14:15], v[14:15], v[40:41]
	s_waitcnt lgkmcnt(0)
	v_pk_add_f32 v[30:31], v[30:31], v[32:33]
	v_cvt_pk_bf16_f32 v17, v14, v15
	v_add_u32_e32 v14, s17, v44
	s_nop 1
	v_mov_b32_dpp v33, v31 quad_perm:[1,0,3,2] row_mask:0xf bank_mask:0xf
	s_nop 1
	v_mov_b32_dpp v32, v30 quad_perm:[1,0,3,2] row_mask:0xf bank_mask:0xf
	v_ashrrev_i32_e32 v15, 31, v14
	v_lshlrev_b64 v[14:15], 11, v[14:15]
	v_lshl_add_u64 v[14:15], s[14:15], 0, v[14:15]
	v_lshl_add_u64 v[14:15], v[14:15], 0, v[18:19]
	global_store_dwordx2 v[14:15], v[16:17], off offset:1024
	s_waitcnt lgkmcnt(0)
	v_pk_add_f32 v[16:17], v[30:31], v[32:33]
	v_add_u32_e32 v14, s17, v25
	v_pk_fma_f32 v[30:31], v[16:17], s[10:11], v[20:21] op_sel_hi:[1,0,0]
	s_nop 0
	v_mul_f32_e32 v15, 0x4b800000, v31
	v_cmp_gt_f32_e32 vcc, s27, v31
	s_nop 1
	v_cndmask_b32_e32 v15, v31, v15, vcc
	v_rsq_f32_e32 v16, v15
	v_ashrrev_i32_e32 v15, 31, v14
	v_lshlrev_b64 v[14:15], 11, v[14:15]
	v_lshl_add_u64 v[14:15], s[14:15], 0, v[14:15]
	v_mul_f32_e32 v17, 0x45800000, v16
	v_cndmask_b32_e32 v16, v16, v17, vcc
	v_pk_mul_f32 v[26:27], v[26:27], v[16:17] op_sel_hi:[1,0]
	v_pk_mul_f32 v[16:17], v[28:29], v[16:17] op_sel_hi:[1,0]
	v_pk_fma_f32 v[26:27], v[2:3], v[26:27], v[6:7]
	v_pk_fma_f32 v[16:17], v[4:5], v[16:17], v[8:9]
	v_mul_f32_e32 v25, 0xbfb8aa3b, v26
	v_exp_f32_e32 v25, v25
	v_mul_f32_e32 v28, 0xbfb8aa3b, v27
	v_exp_f32_e32 v29, v28
	v_lshl_add_u64 v[34:35], v[14:15], 0, v[18:19]
	v_add_f32_e32 v25, 1.0, v25
	v_rcp_f32_e32 v28, v25
	v_add_f32_e32 v25, 1.0, v29
	v_mul_f32_e32 v29, 0xbfb8aa3b, v16
	v_exp_f32_e32 v31, v29
	v_mul_f32_e32 v29, 0xbfb8aa3b, v17
	v_exp_f32_e32 v33, v29
	v_rcp_f32_e32 v29, v25
	v_add_f32_e32 v25, 1.0, v31
	v_rcp_f32_e32 v32, v25
	v_add_f32_e32 v25, 1.0, v33
	v_rcp_f32_e32 v33, v25
	v_pk_mul_f32 v[14:15], v[26:27], v[28:29]
	v_or_b32_e32 v25, 4, v24
	v_cvt_pk_bf16_f32 v36, v14, v15
	v_pk_mul_f32 v[14:15], v[16:17], v[32:33]
	v_lshl_add_u32 v16, v25, 10, v23
	ds_read_b128 v[26:29], v16
	v_cvt_pk_bf16_f32 v37, v14, v15
	v_lshl_add_u32 v14, v42, 10, v23
	ds_read_b128 v[14:17], v14
	v_mul_f32_e32 v33, 0x4b800000, v30
	s_waitcnt lgkmcnt(0)
	v_add_f32_e32 v31, v26, v27
	v_cmp_gt_f32_e32 vcc, s27, v30
	v_add_f32_e32 v31, v28, v31
	v_add_f32_e32 v31, v29, v31
	v_cndmask_b32_e32 v30, v30, v33, vcc
	s_waitcnt lgkmcnt(0)
	v_add_f32_e32 v33, v14, v15
	v_add_f32_e32 v33, v16, v33
	v_mov_b32_e32 v120, v31
	v_mov_b32_e32 v32, v31
	s_nop 1
	v_permlane32_swap_b32_e32 v120, v32
	s_nop 1
	v_permlane32_swap_b32_e32 v32, v120
	s_nop 0
	v_add_f32_e32 v33, v17, v33
	v_mov_b32_e32 v120, v33
	v_mov_b32_e32 v38, v33
	s_nop 1
	v_permlane32_swap_b32_e32 v120, v38
	s_nop 1
	v_permlane32_swap_b32_e32 v38, v120
	s_nop 0
	global_store_dwordx2 v[34:35], v[36:37], off offset:1024
	v_rsq_f32_e32 v30, v30
	s_waitcnt lgkmcnt(0)
	v_add_f32_e32 v31, v31, v32
	v_mov_b32_e32 v120, v31
	v_mov_b32_e32 v32, v31
	s_nop 1
	v_permlane16_swap_b32_e32 v120, v32
	s_nop 1
	v_permlane16_swap_b32_e32 v32, v120
	s_nop 0
	s_waitcnt lgkmcnt(0)
; #define LAS __attribute__((address_space(3)))
; __device__ __forceinline__ unsigned cvtpk(float lo, float hi) { f32x2_t v = {lo, hi}; bf16x2_t b = __builtin_convertvector(v, bf16x2_t); return __builtin_bit_cast(unsigned, b); }
; __device__ __forceinline__ float silu_f(float g) { return g * __builtin_amdgcn_rcpf(1.f + __builtin_amdgcn_exp2f(g * -1.4426950408889634f)); }
; __device__ __forceinline__ float wave_sum(float v) { v += __shfl_xor(v, 32); v += __shfl_xor(v, 16); v += __shfl_xor(v, 8); v += __shfl_xor(v, 4); v += __shfl_xor(v, 2); v += __shfl_xor(v, 1); return v; }
; __device__ void conv_unit(LAS unsigned char* lds, const bf16_t* __restrict__ Z, bf16_t* __restrict__ MIX, int unit,
;                           const float* __restrict__ ccw, const float* __restrict__ ccb, const float* __restrict__ lng, const float* __restrict__ lnb, const float* __restrict__ scw) {
;     ...
;     { const int wid = tid >> 6, lane = tid & 63; const f32x4 gg = *(const f32x4*)(lng + lane * 4), bb = *(const f32x4*)(lnb + lane * 4);
;       for (int j = 0; j < 8; ++j) { const int tok = wid * 8 + j; const f32x4 y = *(LAS const f32x4*)(ub + tok * 256 + lane * 4);
;           const float mean = wave_sum(y[0] + y[1] + y[2] + y[3]) * (1.f / 256.f); const f32x4 d = y - mean;
;           const float var = wave_sum(d[0] * d[0] + d[1] * d[1] + d[2] * d[2] + d[3] * d[3]) * (1.f / 256.f), rstd = rsqrtf(var + 1e-6f);
;           const f32x4 z = d * rstd * gg + bb; u32x2 w; w.x = cvtpk(silu_f(z[0]), silu_f(z[1])); w.y = cvtpk(silu_f(z[2]), silu_f(z[3]));
;           *(u32x2*)(MIX + (size_t)(t0 + tok) * DM + 512 + lane * 4) = w; } }
	v_add_f32_e32 v33, v33, v38
	v_mov_b32_e32 v120, v33
	v_mov_b32_e32 v35, v33
	s_nop 1
	v_permlane16_swap_b32_e32 v120, v35
	s_nop 1
	v_permlane16_swap_b32_e32 v35, v120
	s_nop 0
	v_mul_f32_e32 v34, 0x45800000, v30
	v_cndmask_b32_e32 v30, v30, v34, vcc
	s_waitcnt lgkmcnt(0)
	v_add_f32_e32 v31, v31, v32
	s_nop 1
	v_mov_b32_dpp v32, v31 row_ror:8 row_mask:0xf bank_mask:0xf
	s_waitcnt lgkmcnt(0)
	v_add_f32_e32 v33, v33, v35
	s_nop 1
	v_mov_b32_dpp v34, v33 row_ror:8 row_mask:0xf bank_mask:0xf
	s_waitcnt lgkmcnt(0)
	v_add_f32_e32 v31, v31, v32
	s_nop 1
	v_mov_b32_dpp v121, v31 quad_perm:[3,2,1,0] row_mask:0xf bank_mask:0xf
	s_nop 1
	v_mov_b32_dpp v32, v121 row_half_mirror row_mask:0xf bank_mask:0xf
	s_waitcnt lgkmcnt(0)
	v_add_f32_e32 v33, v33, v34
	s_nop 1
	v_mov_b32_dpp v121, v33 quad_perm:[3,2,1,0] row_mask:0xf bank_mask:0xf
	s_nop 1
	v_mov_b32_dpp v34, v121 row_half_mirror row_mask:0xf bank_mask:0xf
	v_pk_mul_f32 v[10:11], v[10:11], v[30:31] op_sel_hi:[1,0]
	s_waitcnt lgkmcnt(0)
	v_add_f32_e32 v31, v31, v32
	s_nop 1
	v_mov_b32_dpp v32, v31 quad_perm:[2,3,0,1] row_mask:0xf bank_mask:0xf
	s_waitcnt lgkmcnt(0)
	v_add_f32_e32 v33, v33, v34
	s_nop 1
	v_mov_b32_dpp v34, v33 quad_perm:[2,3,0,1] row_mask:0xf bank_mask:0xf
	v_pk_fma_f32 v[10:11], v[2:3], v[10:11], v[6:7]
	s_waitcnt lgkmcnt(0)
	v_add_f32_e32 v31, v31, v32
	s_nop 1
	v_mov_b32_dpp v32, v31 quad_perm:[1,0,3,2] row_mask:0xf bank_mask:0xf
	s_waitcnt lgkmcnt(0)
	v_add_f32_e32 v36, v33, v34
	s_nop 1
	v_mov_b32_dpp v37, v36 quad_perm:[1,0,3,2] row_mask:0xf bank_mask:0xf
	v_mul_f32_e32 v35, 0xbfb8aa3b, v10
	v_exp_f32_e32 v43, v35
	s_waitcnt lgkmcnt(0)
	v_add_f32_e32 v31, v31, v32
	v_fmamk_f32 v27, v31, 0xbb800000, v27
	v_fmamk_f32 v26, v31, 0xbb800000, v26
	v_fmamk_f32 v29, v31, 0xbb800000, v29
	v_fmac_f32_e32 v28, 0xbb800000, v31
	s_waitcnt lgkmcnt(0)
	v_add_f32_e32 v31, v36, v37
	v_mul_f32_e32 v35, 0xbfb8aa3b, v11
	v_fmamk_f32 v15, v31, 0xbb800000, v15
	v_fmamk_f32 v14, v31, 0xbb800000, v14
	v_exp_f32_e32 v44, v35
	v_pk_mul_f32 v[34:35], v[26:27], v[26:27]
	v_fmamk_f32 v17, v31, 0xbb800000, v17
	v_fmac_f32_e32 v16, 0xbb800000, v31
	v_pk_mul_f32 v[38:39], v[14:15], v[14:15]
	v_pk_mul_f32 v[32:33], v[28:29], v[28:29]
	v_pk_mul_f32 v[36:37], v[16:17], v[16:17]
	v_mov_b32_e32 v40, v38
	v_mov_b32_e32 v41, v34
	v_mov_b32_e32 v34, v39
	v_pk_add_f32 v[34:35], v[40:41], v[34:35]
	v_mov_b32_e32 v38, v36
	v_mov_b32_e32 v39, v32
	v_pk_add_f32 v[34:35], v[38:39], v[34:35]
	v_mov_b32_e32 v32, v37
	v_pk_add_f32 v[32:33], v[32:33], v[34:35]
	v_mov_b32_e32 v120, v33
	v_mov_b32_e32 v35, v33
	s_nop 1
	v_permlane32_swap_b32_e32 v120, v35
	s_nop 1
	v_permlane32_swap_b32_e32 v35, v120
	s_nop 0
	v_mov_b32_e32 v120, v32
	v_mov_b32_e32 v34, v32
	s_nop 1
	v_permlane32_swap_b32_e32 v120, v34
	s_nop 1
	v_permlane32_swap_b32_e32 v34, v120
	s_nop 0
	v_add_f32_e32 v31, 1.0, v43
	v_rcp_f32_e32 v36, v31
	v_add_f32_e32 v31, 1.0, v44
	v_rcp_f32_e32 v37, v31
	s_waitcnt lgkmcnt(0)
	v_pk_add_f32 v[32:33], v[32:33], v[34:35]
	v_mov_b32_e32 v120, v33
	v_mov_b32_e32 v35, v33
	s_nop 1
	v_permlane16_swap_b32_e32 v120, v35
	s_nop 1
	v_permlane16_swap_b32_e32 v35, v120
	s_nop 0
	v_mov_b32_e32 v120, v32
	v_mov_b32_e32 v34, v32
	s_nop 1
	v_permlane16_swap_b32_e32 v120, v34
	s_nop 1
	v_permlane16_swap_b32_e32 v34, v120
	s_nop 0
	v_pk_mul_f32 v[12:13], v[12:13], v[30:31] op_sel_hi:[1,0]
	v_pk_mul_f32 v[10:11], v[10:11], v[36:37]
	v_pk_fma_f32 v[12:13], v[4:5], v[12:13], v[8:9]
	v_cvt_pk_bf16_f32 v10, v10, v11
	s_waitcnt lgkmcnt(0)
	v_pk_add_f32 v[30:31], v[32:33], v[34:35]
	s_nop 1
	v_mov_b32_dpp v33, v31 row_ror:8 row_mask:0xf bank_mask:0xf
	s_nop 1
	v_mov_b32_dpp v32, v30 row_ror:8 row_mask:0xf bank_mask:0xf
	v_mul_f32_e32 v11, 0xbfb8aa3b, v12
	v_exp_f32_e32 v11, v11
	v_mul_f32_e32 v34, 0xbfb8aa3b, v13
	v_exp_f32_e32 v35, v34
	s_waitcnt lgkmcnt(0)
	v_pk_add_f32 v[30:31], v[30:31], v[32:33]
	s_nop 1
	v_mov_b32_dpp v121, v31 quad_perm:[3,2,1,0] row_mask:0xf bank_mask:0xf
	s_nop 1
	v_mov_b32_dpp v33, v121 row_half_mirror row_mask:0xf bank_mask:0xf
	s_nop 1
	v_mov_b32_dpp v121, v30 quad_perm:[3,2,1,0] row_mask:0xf bank_mask:0xf
	s_nop 1
	v_mov_b32_dpp v32, v121 row_half_mirror row_mask:0xf bank_mask:0xf
	v_add_f32_e32 v11, 1.0, v11
	v_rcp_f32_e32 v34, v11
	v_add_f32_e32 v11, 1.0, v35
	v_rcp_f32_e32 v35, v11
	s_waitcnt lgkmcnt(0)
	v_pk_add_f32 v[30:31], v[30:31], v[32:33]
	s_nop 1
	v_mov_b32_dpp v33, v31 quad_perm:[2,3,0,1] row_mask:0xf bank_mask:0xf
	s_nop 1
	v_mov_b32_dpp v32, v30 quad_perm:[2,3,0,1] row_mask:0xf bank_mask:0xf
	v_pk_mul_f32 v[12:13], v[12:13], v[34:35]
	v_or_b32_e32 v36, 6, v24
	v_cvt_pk_bf16_f32 v11, v12, v13
	v_add_u32_e32 v12, s17, v45
	s_waitcnt lgkmcnt(0)
	v_pk_add_f32 v[30:31], v[30:31], v[32:33]
	s_nop 1
	v_mov_b32_dpp v33, v31 quad_perm:[1,0,3,2] row_mask:0xf bank_mask:0xf
	s_nop 1
	v_mov_b32_dpp v32, v30 quad_perm:[1,0,3,2] row_mask:0xf bank_mask:0xf
	v_ashrrev_i32_e32 v13, 31, v12
	v_lshlrev_b64 v[12:13], 11, v[12:13]
	v_lshl_add_u64 v[12:13], s[14:15], 0, v[12:13]
	v_lshl_add_u64 v[12:13], v[12:13], 0, v[18:19]
	global_store_dwordx2 v[12:13], v[10:11], off offset:1024
	s_waitcnt lgkmcnt(0)
; #define LAS __attribute__((address_space(3)))
; __device__ __forceinline__ unsigned cvtpk(float lo, float hi) { f32x2_t v = {lo, hi}; bf16x2_t b = __builtin_convertvector(v, bf16x2_t); return __builtin_bit_cast(unsigned, b); }
; __device__ __forceinline__ float silu_f(float g) { return g * __builtin_amdgcn_rcpf(1.f + __builtin_amdgcn_exp2f(g * -1.4426950408889634f)); }
; __device__ __forceinline__ float wave_sum(float v) { v += __shfl_xor(v, 32); v += __shfl_xor(v, 16); v += __shfl_xor(v, 8); v += __shfl_xor(v, 4); v += __shfl_xor(v, 2); v += __shfl_xor(v, 1); return v; }
; __device__ void conv_unit(LAS unsigned char* lds, const bf16_t* __restrict__ Z, bf16_t* __restrict__ MIX, int unit,
;                           const float* __restrict__ ccw, const float* __restrict__ ccb, const float* __restrict__ lng, const float* __restrict__ lnb, const float* __restrict__ scw) {
;     ...
;     { const int wid = tid >> 6, lane = tid & 63; const f32x4 gg = *(const f32x4*)(lng + lane * 4), bb = *(const f32x4*)(lnb + lane * 4);
;       for (int j = 0; j < 8; ++j) { const int tok = wid * 8 + j; const f32x4 y = *(LAS const f32x4*)(ub + tok * 256 + lane * 4);
;           const float mean = wave_sum(y[0] + y[1] + y[2] + y[3]) * (1.f / 256.f); const f32x4 d = y - mean;
;           const float var = wave_sum(d[0] * d[0] + d[1] * d[1] + d[2] * d[2] + d[3] * d[3]) * (1.f / 256.f), rstd = rsqrtf(var + 1e-6f);
;           const f32x4 z = d * rstd * gg + bb; u32x2 w; w.x = cvtpk(silu_f(z[0]), silu_f(z[1])); w.y = cvtpk(silu_f(z[2]), silu_f(z[3]));
;           *(u32x2*)(MIX + (size_t)(t0 + tok) * DM + 512 + lane * 4) = w; } }
	v_pk_add_f32 v[10:11], v[30:31], v[32:33]
	v_or_b32_e32 v37, 7, v22
	v_pk_fma_f32 v[10:11], v[10:11], s[10:11], v[20:21] op_sel_hi:[1,0,0]
	v_lshl_add_u32 v22, v37, 10, v23
	v_mul_f32_e32 v12, 0x4b800000, v11
	v_cmp_gt_f32_e32 vcc, s27, v11
	s_nop 1
	v_cndmask_b32_e32 v11, v11, v12, vcc
	v_rsq_f32_e32 v11, v11
	v_add_u32_e32 v12, s17, v25
	v_ashrrev_i32_e32 v13, 31, v12
	v_lshlrev_b64 v[12:13], 11, v[12:13]
	v_mul_f32_e32 v25, 0x45800000, v11
	v_cndmask_b32_e32 v30, v11, v25, vcc
	v_pk_mul_f32 v[26:27], v[26:27], v[30:31] op_sel_hi:[1,0]
	v_lshl_add_u64 v[12:13], s[14:15], 0, v[12:13]
	v_pk_fma_f32 v[26:27], v[2:3], v[26:27], v[6:7]
	v_lshl_add_u64 v[34:35], v[12:13], 0, v[18:19]
	v_mul_f32_e32 v11, 0xbfb8aa3b, v26
	v_exp_f32_e32 v11, v11
	v_mul_f32_e32 v25, 0xbfb8aa3b, v27
	v_exp_f32_e32 v25, v25
	v_pk_mul_f32 v[12:13], v[28:29], v[30:31] op_sel_hi:[1,0]
	v_add_f32_e32 v11, 1.0, v11
	v_rcp_f32_e32 v32, v11
	v_add_f32_e32 v11, 1.0, v25
	v_pk_fma_f32 v[28:29], v[4:5], v[12:13], v[8:9]
	v_rcp_f32_e32 v33, v11
	v_mul_f32_e32 v11, 0xbfb8aa3b, v28
	v_exp_f32_e32 v11, v11
	v_mul_f32_e32 v25, 0xbfb8aa3b, v29
	v_exp_f32_e32 v25, v25
	v_cmp_gt_f32_e32 vcc, s27, v10
	v_add_f32_e32 v11, 1.0, v11
	v_rcp_f32_e32 v30, v11
	v_add_f32_e32 v11, 1.0, v25
	v_rcp_f32_e32 v31, v11
	v_mul_f32_e32 v11, 0x4b800000, v10
	v_pk_mul_f32 v[12:13], v[26:27], v[32:33]
	v_cndmask_b32_e32 v25, v10, v11, vcc
	v_lshl_add_u32 v10, v36, 10, v23
	v_cvt_pk_bf16_f32 v26, v12, v13
	ds_read_b128 v[10:13], v10
	v_rsq_f32_e32 v32, v25
	ds_read_b128 v[22:25], v22
	v_pk_mul_f32 v[28:29], v[28:29], v[30:31]
	s_waitcnt lgkmcnt(0)
	v_add_f32_e32 v27, v10, v11
	v_add_f32_e32 v27, v12, v27
	v_add_f32_e32 v33, v13, v27
	v_mov_b32_e32 v120, v33
	v_mov_b32_e32 v38, v33
	s_nop 1
	v_permlane32_swap_b32_e32 v120, v38
	s_nop 1
	v_permlane32_swap_b32_e32 v38, v120
	s_nop 0
	v_cvt_pk_bf16_f32 v27, v28, v29
	s_waitcnt lgkmcnt(0)
	v_add_f32_e32 v29, v22, v23
	v_add_f32_e32 v29, v24, v29
	global_store_dwordx2 v[34:35], v[26:27], off offset:1024
	s_waitcnt lgkmcnt(0)
	v_add_f32_e32 v27, v33, v38
	v_add_f32_e32 v29, v25, v29
	v_mov_b32_e32 v120, v27
	v_mov_b32_e32 v28, v27
	s_nop 1
	v_permlane16_swap_b32_e32 v120, v28
	s_nop 1
	v_permlane16_swap_b32_e32 v28, v120
	s_nop 0
	v_mov_b32_e32 v120, v29
	v_mov_b32_e32 v30, v29
	s_nop 1
	v_permlane32_swap_b32_e32 v120, v30
	s_nop 1
	v_permlane32_swap_b32_e32 v30, v120
	s_nop 0
	v_mul_f32_e32 v26, 0x45800000, v32
	v_cndmask_b32_e32 v26, v32, v26, vcc
	s_waitcnt lgkmcnt(0)
	v_add_f32_e32 v27, v27, v28
	s_waitcnt lgkmcnt(0)
	v_add_f32_e32 v29, v29, v30
	s_nop 1
	v_mov_b32_dpp v28, v27 row_ror:8 row_mask:0xf bank_mask:0xf
	v_mov_b32_e32 v120, v29
	v_mov_b32_e32 v30, v29
	s_nop 1
	v_permlane16_swap_b32_e32 v120, v30
	s_nop 1
	v_permlane16_swap_b32_e32 v30, v120
	s_nop 0
	v_pk_mul_f32 v[14:15], v[14:15], v[26:27] op_sel_hi:[1,0]
	v_pk_mul_f32 v[16:17], v[16:17], v[26:27] op_sel_hi:[1,0]
	v_pk_fma_f32 v[14:15], v[2:3], v[14:15], v[6:7]
	s_waitcnt lgkmcnt(0)
	v_add_f32_e32 v26, v27, v28
	s_waitcnt lgkmcnt(0)
	v_add_f32_e32 v28, v29, v30
	s_nop 1
	v_mov_b32_dpp v29, v28 row_ror:8 row_mask:0xf bank_mask:0xf
	s_nop 1
	v_mov_b32_dpp v121, v26 quad_perm:[3,2,1,0] row_mask:0xf bank_mask:0xf
	s_nop 1
	v_mov_b32_dpp v27, v121 row_half_mirror row_mask:0xf bank_mask:0xf
	v_mul_f32_e32 v30, 0xbfb8aa3b, v14
	v_exp_f32_e32 v38, v30
	v_mul_f32_e32 v30, 0xbfb8aa3b, v15
	s_waitcnt lgkmcnt(0)
	v_add_f32_e32 v28, v28, v29
	s_nop 1
	v_mov_b32_dpp v121, v28 quad_perm:[3,2,1,0] row_mask:0xf bank_mask:0xf
	s_nop 1
	v_mov_b32_dpp v29, v121 row_half_mirror row_mask:0xf bank_mask:0xf
	s_waitcnt lgkmcnt(0)
	v_add_f32_e32 v26, v26, v27
	s_nop 1
	v_mov_b32_dpp v27, v26 quad_perm:[2,3,0,1] row_mask:0xf bank_mask:0xf
	v_exp_f32_e32 v39, v30
	v_pk_fma_f32 v[16:17], v[4:5], v[16:17], v[8:9]
	s_waitcnt lgkmcnt(0)
	v_add_f32_e32 v28, v28, v29
	s_nop 1
	v_mov_b32_dpp v29, v28 quad_perm:[2,3,0,1] row_mask:0xf bank_mask:0xf
	s_waitcnt lgkmcnt(0)
	v_add_f32_e32 v26, v26, v27
	s_nop 1
	v_mov_b32_dpp v27, v26 quad_perm:[1,0,3,2] row_mask:0xf bank_mask:0xf
	s_waitcnt lgkmcnt(0)
	v_add_f32_e32 v30, v28, v29
	s_nop 1
	v_mov_b32_dpp v31, v30 quad_perm:[1,0,3,2] row_mask:0xf bank_mask:0xf
	s_waitcnt lgkmcnt(0)
	v_add_f32_e32 v26, v26, v27
	v_fmamk_f32 v11, v26, 0xbb800000, v11
	v_fmamk_f32 v10, v26, 0xbb800000, v10
	v_fmamk_f32 v13, v26, 0xbb800000, v13
	s_waitcnt lgkmcnt(0)
	v_add_f32_e32 v30, v30, v31
	v_fmamk_f32 v23, v30, 0xbb800000, v23
	v_fmamk_f32 v22, v30, 0xbb800000, v22
	v_fmac_f32_e32 v12, 0xbb800000, v26
	v_pk_mul_f32 v[28:29], v[10:11], v[10:11]
	v_fmamk_f32 v25, v30, 0xbb800000, v25
	v_fmac_f32_e32 v24, 0xbb800000, v30
	v_pk_mul_f32 v[32:33], v[22:23], v[22:23]
	v_pk_mul_f32 v[26:27], v[12:13], v[12:13]
	v_pk_mul_f32 v[30:31], v[24:25], v[24:25]
	v_mov_b32_e32 v34, v32
	v_mov_b32_e32 v35, v28
	v_mov_b32_e32 v28, v33
	v_pk_add_f32 v[28:29], v[34:35], v[28:29]
	v_mov_b32_e32 v32, v30
	v_mov_b32_e32 v33, v26
	v_pk_add_f32 v[28:29], v[32:33], v[28:29]
	v_mov_b32_e32 v26, v31
	v_pk_add_f32 v[26:27], v[26:27], v[28:29]
	v_mov_b32_e32 v120, v27
	v_mov_b32_e32 v29, v27
	s_nop 1
	v_permlane32_swap_b32_e32 v120, v29
	s_nop 1
	v_permlane32_swap_b32_e32 v29, v120
	s_nop 0
	v_mov_b32_e32 v120, v26
	v_mov_b32_e32 v28, v26
	s_nop 1
	v_permlane32_swap_b32_e32 v120, v28
	s_nop 1
	v_permlane32_swap_b32_e32 v28, v120
	s_nop 0
	v_mul_f32_e32 v32, 0xbfb8aa3b, v16
	v_mul_f32_e32 v33, 0xbfb8aa3b, v17
	v_exp_f32_e32 v32, v32
	v_exp_f32_e32 v33, v33
	s_waitcnt lgkmcnt(0)
; #define LAS __attribute__((address_space(3)))
; __device__ __forceinline__ unsigned cvtpk(float lo, float hi) { f32x2_t v = {lo, hi}; bf16x2_t b = __builtin_convertvector(v, bf16x2_t); return __builtin_bit_cast(unsigned, b); }
; __device__ __forceinline__ float silu_f(float g) { return g * __builtin_amdgcn_rcpf(1.f + __builtin_amdgcn_exp2f(g * -1.4426950408889634f)); }
; __device__ __forceinline__ float wave_sum(float v) { v += __shfl_xor(v, 32); v += __shfl_xor(v, 16); v += __shfl_xor(v, 8); v += __shfl_xor(v, 4); v += __shfl_xor(v, 2); v += __shfl_xor(v, 1); return v; }
; __device__ void conv_unit(LAS unsigned char* lds, const bf16_t* __restrict__ Z, bf16_t* __restrict__ MIX, int unit,
;                           const float* __restrict__ ccw, const float* __restrict__ ccb, const float* __restrict__ lng, const float* __restrict__ lnb, const float* __restrict__ scw) {
;     ...
;     { const int wid = tid >> 6, lane = tid & 63; const f32x4 gg = *(const f32x4*)(lng + lane * 4), bb = *(const f32x4*)(lnb + lane * 4);
;       for (int j = 0; j < 8; ++j) { const int tok = wid * 8 + j; const f32x4 y = *(LAS const f32x4*)(ub + tok * 256 + lane * 4);
;           const float mean = wave_sum(y[0] + y[1] + y[2] + y[3]) * (1.f / 256.f); const f32x4 d = y - mean;
;           const float var = wave_sum(d[0] * d[0] + d[1] * d[1] + d[2] * d[2] + d[3] * d[3]) * (1.f / 256.f), rstd = rsqrtf(var + 1e-6f);
;           const f32x4 z = d * rstd * gg + bb; u32x2 w; w.x = cvtpk(silu_f(z[0]), silu_f(z[1])); w.y = cvtpk(silu_f(z[2]), silu_f(z[3]));
;           *(u32x2*)(MIX + (size_t)(t0 + tok) * DM + 512 + lane * 4) = w; } }
	v_pk_add_f32 v[26:27], v[26:27], v[28:29]
	v_mov_b32_e32 v120, v27
	v_mov_b32_e32 v29, v27
	s_nop 1
	v_permlane16_swap_b32_e32 v120, v29
	s_nop 1
	v_permlane16_swap_b32_e32 v29, v120
	s_nop 0
	v_mov_b32_e32 v120, v26
	v_mov_b32_e32 v28, v26
	s_nop 1
	v_permlane16_swap_b32_e32 v120, v28
	s_nop 1
	v_permlane16_swap_b32_e32 v28, v120
	s_nop 0
	v_add_f32_e32 v30, 1.0, v38
	v_add_f32_e32 v31, 1.0, v39
	v_add_f32_e32 v32, 1.0, v32
	v_add_f32_e32 v33, 1.0, v33
	s_waitcnt lgkmcnt(0)
	v_pk_add_f32 v[26:27], v[26:27], v[28:29]
	s_nop 1
	v_mov_b32_dpp v29, v27 row_ror:8 row_mask:0xf bank_mask:0xf
	s_nop 1
	v_mov_b32_dpp v28, v26 row_ror:8 row_mask:0xf bank_mask:0xf
	v_rcp_f32_e32 v30, v30
	v_rcp_f32_e32 v31, v31
	v_rcp_f32_e32 v32, v32
	v_rcp_f32_e32 v33, v33
	s_waitcnt lgkmcnt(0)
	v_pk_add_f32 v[26:27], v[26:27], v[28:29]
	s_nop 1
	v_mov_b32_dpp v121, v27 quad_perm:[3,2,1,0] row_mask:0xf bank_mask:0xf
	s_nop 1
	v_mov_b32_dpp v29, v121 row_half_mirror row_mask:0xf bank_mask:0xf
	s_nop 1
	v_mov_b32_dpp v121, v26 quad_perm:[3,2,1,0] row_mask:0xf bank_mask:0xf
	s_nop 1
	v_mov_b32_dpp v28, v121 row_half_mirror row_mask:0xf bank_mask:0xf
	v_pk_mul_f32 v[14:15], v[14:15], v[30:31]
	v_pk_mul_f32 v[16:17], v[16:17], v[32:33]
	v_cvt_pk_bf16_f32 v14, v14, v15
	v_cvt_pk_bf16_f32 v15, v16, v17
	s_waitcnt lgkmcnt(0)
	v_pk_add_f32 v[16:17], v[26:27], v[28:29]
	s_nop 1
	v_mov_b32_dpp v27, v17 quad_perm:[2,3,0,1] row_mask:0xf bank_mask:0xf
	s_nop 1
	v_mov_b32_dpp v26, v16 quad_perm:[2,3,0,1] row_mask:0xf bank_mask:0xf
	v_add_u32_e32 v28, s17, v42
	v_ashrrev_i32_e32 v29, 31, v28
	v_lshlrev_b64 v[28:29], 11, v[28:29]
	v_lshl_add_u64 v[28:29], s[14:15], 0, v[28:29]
	s_waitcnt lgkmcnt(0)
	v_pk_add_f32 v[16:17], v[16:17], v[26:27]
	s_nop 1
	v_mov_b32_dpp v27, v17 quad_perm:[1,0,3,2] row_mask:0xf bank_mask:0xf
	s_nop 1
	v_mov_b32_dpp v26, v16 quad_perm:[1,0,3,2] row_mask:0xf bank_mask:0xf
	v_lshl_add_u64 v[28:29], v[28:29], 0, v[18:19]
	global_store_dwordx2 v[28:29], v[14:15], off offset:1024
	v_add_u32_e32 v14, s17, v36
	v_ashrrev_i32_e32 v15, 31, v14
	s_waitcnt lgkmcnt(0)
	v_pk_add_f32 v[16:17], v[16:17], v[26:27]
	v_lshlrev_b64 v[14:15], 11, v[14:15]
	v_pk_fma_f32 v[16:17], v[16:17], s[10:11], v[20:21] op_sel_hi:[1,0,0]
	v_lshl_add_u64 v[14:15], s[14:15], 0, v[14:15]
	v_mul_f32_e32 v20, 0x4b800000, v17
	v_cmp_gt_f32_e32 vcc, s27, v17
	v_lshl_add_u64 v[14:15], v[14:15], 0, v[18:19]
	s_mov_b32 s10, 0
	v_cndmask_b32_e32 v17, v17, v20, vcc
	v_rsq_f32_e32 v17, v17
	s_nop 0
	v_mul_f32_e32 v20, 0x45800000, v17
	v_cndmask_b32_e32 v20, v17, v20, vcc
	v_pk_mul_f32 v[10:11], v[10:11], v[20:21] op_sel_hi:[1,0]
	v_pk_mul_f32 v[12:13], v[12:13], v[20:21] op_sel_hi:[1,0]
	v_pk_fma_f32 v[10:11], v[2:3], v[10:11], v[6:7]
	v_pk_fma_f32 v[12:13], v[4:5], v[12:13], v[8:9]
	v_mul_f32_e32 v17, 0xbfb8aa3b, v10
	v_exp_f32_e32 v17, v17
	v_mul_f32_e32 v20, 0xbfb8aa3b, v11
	v_exp_f32_e32 v21, v20
	v_mul_f32_e32 v26, 0xbfb8aa3b, v13
	v_add_f32_e32 v17, 1.0, v17
	v_rcp_f32_e32 v20, v17
	v_add_f32_e32 v17, 1.0, v21
	v_rcp_f32_e32 v21, v17
	v_mul_f32_e32 v17, 0xbfb8aa3b, v12
	v_exp_f32_e32 v17, v17
	v_exp_f32_e32 v26, v26
	v_pk_mul_f32 v[10:11], v[10:11], v[20:21]
	v_cmp_gt_f32_e32 vcc, s27, v16
	v_add_f32_e32 v17, 1.0, v17
	v_rcp_f32_e32 v20, v17
	v_add_f32_e32 v17, 1.0, v26
	v_rcp_f32_e32 v21, v17
	v_mul_f32_e32 v17, 0x4b800000, v16
	v_cndmask_b32_e32 v16, v16, v17, vcc
	v_rsq_f32_e32 v16, v16
	v_pk_mul_f32 v[12:13], v[12:13], v[20:21]
	v_cvt_pk_bf16_f32 v10, v10, v11
	v_cvt_pk_bf16_f32 v11, v12, v13
	v_mul_f32_e32 v12, 0x45800000, v16
	v_cndmask_b32_e32 v12, v16, v12, vcc
	v_pk_mul_f32 v[16:17], v[22:23], v[12:13] op_sel_hi:[1,0]
	v_pk_mul_f32 v[12:13], v[24:25], v[12:13] op_sel_hi:[1,0]
	v_pk_fma_f32 v[2:3], v[2:3], v[16:17], v[6:7]
	v_pk_fma_f32 v[4:5], v[4:5], v[12:13], v[8:9]
	v_mul_f32_e32 v6, 0xbfb8aa3b, v2
	v_mul_f32_e32 v7, 0xbfb8aa3b, v3
	v_mul_f32_e32 v8, 0xbfb8aa3b, v4
	v_mul_f32_e32 v9, 0xbfb8aa3b, v5
	v_exp_f32_e32 v6, v6
	v_exp_f32_e32 v7, v7
	v_exp_f32_e32 v8, v8
	v_exp_f32_e32 v9, v9
	v_add_f32_e32 v6, 1.0, v6
	v_add_f32_e32 v7, 1.0, v7
	v_add_f32_e32 v8, 1.0, v8
	v_add_f32_e32 v9, 1.0, v9
	v_rcp_f32_e32 v6, v6
	v_rcp_f32_e32 v7, v7
	v_rcp_f32_e32 v8, v8
	v_rcp_f32_e32 v9, v9
	global_store_dwordx2 v[14:15], v[10:11], off offset:1024
	v_pk_mul_f32 v[2:3], v[2:3], v[6:7]
	v_lshlrev_b32_e32 v22, 2, v101
	v_pk_mul_f32 v[4:5], v[4:5], v[8:9]
	v_cvt_pk_bf16_f32 v2, v2, v3
	v_cvt_pk_bf16_f32 v3, v4, v5
	v_add_u32_e32 v4, s17, v37
	v_ashrrev_i32_e32 v5, 31, v4
	v_lshlrev_b64 v[4:5], 11, v[4:5]
	v_lshl_add_u64 v[4:5], s[14:15], 0, v[4:5]
	v_lshl_add_u64 v[4:5], v[4:5], 0, v[18:19]
	global_store_dwordx2 v[4:5], v[2:3], off offset:1024
	global_load_dwordx4 v[2:5], v22, s[40:41] offset:16
	s_nop 0
	global_load_dwordx4 v[6:9], v22, s[40:41]
	global_load_dwordx4 v[10:13], v22, s[40:41] offset:1040
	global_load_dwordx4 v[14:17], v22, s[40:41] offset:1024
	global_load_dwordx4 v[18:21], v22, s[40:41] offset:2064
	s_nop 0
	global_load_dwordx4 v[22:25], v22, s[40:41] offset:2048
	v_lshl_add_u64 v[26:27], s[14:15], 0, v[0:1]
